# attnA fixed-softmax loop: next pair K/V LDS staging issued before the second tile PV MFMAs
# speedup vs baseline: 1.0267x; 1.0001x over previous
; #define LAS __attribute__((address_space(3)))
; __device__ __forceinline__ unsigned cvtpk(float lo, float hi) { f32x2_t v = {lo, hi}; bf16x2_t b = __builtin_convertvector(v, bf16x2_t); return __builtin_bit_cast(unsigned, b); }
; __device__ __forceinline__ int pi_row(int i) { return (i & ~12) | ((i & 4) << 1) | ((i & 8) >> 1); }
; #define MFMA32(a, b, c) __builtin_amdgcn_mfma_f32_32x32x16_bf16((a), (b), (c), 0, 0, 0)
; template <bool INIT = true> __device__ __forceinline__ void qk_lds(f32x16& p0, f32x16& p1, const LAS unsigned char* buf, const bf16x8 (&qr)[4], int r32, int hi) {
;     const LAS unsigned char* kp = buf + pi_row(r32) * TP + hi * 16;
;     if (INIT) { p0 = (f32x16){}; p1 = (f32x16){}; }
;     bf16x8 kf[8];
; #pragma unroll
;     for (int d0 = 0; d0 < 4; ++d0) { kf[2 * d0] = *(const LAS bf16x8*)(kp + d0 * 32); kf[2 * d0 + 1] = *(const LAS bf16x8*)(kp + 32 * TP + d0 * 32); }
;     __builtin_amdgcn_s_setprio(1);
; #pragma unroll
;     for (int d0 = 0; d0 < 4; ++d0) { p0 = MFMA32(kf[2 * d0], qr[d0], p0); p1 = MFMA32(kf[2 * d0 + 1], qr[d0], p1); }
;     __builtin_amdgcn_s_setprio(0);
; }
; __device__ __forceinline__ void pv_lds(f32x16& o0, f32x16& o1, const LAS unsigned char* buf, const f32x16& p0, const f32x16& p1, int r32, int hi) {
;     const LAS unsigned char* vp = buf + TILE_B + r32 * TP + hi * 16;
;     bf16x8 pf[4], vf[8];
; #pragma unroll
;     for (int half = 0; half < 2; ++half)
; #pragma unroll
;         for (int s = 0; s < 2; ++s) {
;             const f32x16& p = half ? p1 : p0;
;             u32x4 w; w.x = cvtpk(p[8 * s + 0], p[8 * s + 1]); w.y = cvtpk(p[8 * s + 2], p[8 * s + 3]); w.z = cvtpk(p[8 * s + 4], p[8 * s + 5]); w.w = cvtpk(p[8 * s + 6], p[8 * s + 7]);
;             pf[half * 2 + s] = __builtin_bit_cast(bf16x8, w);
;             vf[(half * 2 + s) * 2] = *(const LAS bf16x8*)(vp + half * 64 + s * 32); vf[(half * 2 + s) * 2 + 1] = *(const LAS bf16x8*)(vp + 32 * TP + half * 64 + s * 32);
;         }
;     __builtin_amdgcn_s_setprio(1);
; #pragma unroll
;     for (int k = 0; k < 4; ++k) { o0 = MFMA32(vf[2 * k], pf[k], o0); o1 = MFMA32(vf[2 * k + 1], pf[k], o1); }
;     __builtin_amdgcn_s_setprio(0);
; }
.LBB0_512:
	v_add3_u32 v0, s28, v137, v138
	ds_read_b128 v[2:5], v0 offset:18432
	ds_read_b128 v[6:9], v0 offset:18464
	ds_read_b128 v[10:13], v0 offset:23040
	ds_read_b128 v[204:207], v0 offset:23072
	ds_read_b128 v[208:211], v0 offset:18496
	ds_read_b128 v[216:219], v0 offset:18528
	ds_read_b128 v[220:223], v0 offset:23104
	ds_read_b128 v[224:227], v0 offset:23136
	s_setprio 1
	s_waitcnt lgkmcnt(7)
	v_mfma_f32_32x32x16_bf16 v[64:79], v[2:5], v[84:87], v[64:79]
	s_waitcnt lgkmcnt(5)
	v_mfma_f32_32x32x16_bf16 v[48:63], v[10:13], v[84:87], v[48:63]
	v_mfma_f32_32x32x16_bf16 v[64:79], v[6:9], v[88:91], v[64:79]
	s_waitcnt lgkmcnt(4)
	v_mfma_f32_32x32x16_bf16 v[48:63], v[204:207], v[88:91], v[48:63]
	s_waitcnt lgkmcnt(3)
	v_mfma_f32_32x32x16_bf16 v[64:79], v[208:211], v[96:99], v[64:79]
	s_waitcnt lgkmcnt(1)
	v_mfma_f32_32x32x16_bf16 v[48:63], v[220:223], v[96:99], v[48:63]
	v_mfma_f32_32x32x16_bf16 v[64:79], v[216:219], v[100:103], v[64:79]
	s_waitcnt lgkmcnt(0)
	v_mfma_f32_32x32x16_bf16 v[48:63], v[224:227], v[100:103], v[48:63]
	s_setprio 0
	s_nop 8
	v_exp_f32_e32 v206, v64
	s_nop 0
	v_exp_f32_e32 v207, v48
	v_exp_f32_e32 v2, v65
	v_exp_f32_e32 v0, v49
	v_exp_f32_e32 v208, v50
	v_add_f32_e32 v3, v206, v207
	v_pk_add_f32 v[4:5], v[2:3], v[0:1]
	s_nop 0
	v_pk_add_f32 v[14:15], v[4:5], v[4:5] op_sel_hi:[0,1]
	v_exp_f32_e32 v3, v66
	v_exp_f32_e32 v4, v67
	v_exp_f32_e32 v14, v51
	v_cvt_pk_bf16_f32 v2, v206, v2
	v_add_f32_e32 v5, v3, v208
	v_cvt_pk_bf16_f32 v3, v3, v4
	v_pk_add_f32 v[6:7], v[4:5], v[14:15]
	v_exp_f32_e32 v5, v68
	v_pk_add_f32 v[64:65], v[6:7], v[6:7] op_sel_hi:[0,1]
	v_exp_f32_e32 v15, v52
	v_exp_f32_e32 v6, v69
	v_exp_f32_e32 v64, v53
	v_add_f32_e32 v7, v5, v15
	v_cvt_pk_bf16_f32 v4, v5, v6
	v_pk_add_f32 v[8:9], v[6:7], v[64:65]
	v_exp_f32_e32 v7, v70
	v_pk_add_f32 v[66:67], v[8:9], v[8:9] op_sel_hi:[0,1]
	v_exp_f32_e32 v65, v54
	v_exp_f32_e32 v8, v71
	v_exp_f32_e32 v66, v55
	v_exp_f32_e32 v54, v72
	v_add_f32_e32 v9, v7, v65
	v_exp_f32_e32 v72, v56
	v_pk_add_f32 v[10:11], v[8:9], v[66:67]
	v_cvt_pk_bf16_f32 v5, v7, v8
	v_pk_add_f32 v[202:203], v[10:11], v[10:11] op_sel_hi:[0,1]
	v_exp_f32_e32 v10, v73
	v_exp_f32_e32 v202, v57
	v_add_f32_e32 v11, v54, v72
	v_exp_f32_e32 v73, v58
	v_pk_add_f32 v[12:13], v[10:11], v[202:203]
	s_nop 0
	v_pk_add_f32 v[204:205], v[12:13], v[12:13] op_sel_hi:[0,1]
	v_exp_f32_e32 v11, v74
	v_exp_f32_e32 v12, v75
	v_exp_f32_e32 v204, v59
	v_exp_f32_e32 v203, v60
	v_add_f32_e32 v13, v11, v73
	v_cvt_pk_bf16_f32 v10, v54, v10
	v_pk_add_f32 v[48:49], v[12:13], v[204:205]
	v_exp_f32_e32 v13, v76
	v_pk_add_f32 v[74:75], v[48:49], v[48:49] op_sel_hi:[0,1]
	v_exp_f32_e32 v48, v77
	v_exp_f32_e32 v74, v61
	v_add_f32_e32 v49, v13, v203
	v_add3_u32 v205, s28, v139, v138
	v_cvt_pk_bf16_f32 v11, v11, v12
	v_pk_add_f32 v[50:51], v[48:49], v[74:75]
	v_exp_f32_e32 v49, v78
	v_pk_add_f32 v[76:77], v[50:51], v[50:51] op_sel_hi:[0,1]
	v_exp_f32_e32 v75, v62
	v_exp_f32_e32 v50, v79
	v_exp_f32_e32 v76, v63
	v_cvt_pk_bf16_f32 v12, v13, v48
	v_add_f32_e32 v51, v49, v75
	v_cvt_pk_bf16_f32 v13, v49, v50
	v_pk_add_f32 v[52:53], v[50:51], v[76:77]
	v_cvt_pk_bf16_f32 v60, v207, v0
	v_add_f32_e32 v9, v52, v53
	v_add_f32_e32 v214, v214, v9
	ds_read_b128 v[6:9], v205 offset:32256
	ds_read_b128 v[48:51], v205 offset:27648
	ds_read_b128 v[52:55], v205 offset:27680
	ds_read_b128 v[56:59], v205 offset:32288
	v_cvt_pk_bf16_f32 v62, v15, v64
	v_cvt_pk_bf16_f32 v63, v65, v66
	ds_read_b128 v[64:67], v205 offset:27712
	ds_read_b128 v[68:71], v205 offset:32320
	v_cvt_pk_bf16_f32 v73, v73, v204
	v_cvt_pk_bf16_f32 v75, v75, v76
	ds_read_b128 v[76:79], v205 offset:27744
	ds_read_b128 v[204:207], v205 offset:32352
	v_cvt_pk_bf16_f32 v61, v208, v14
	v_cvt_pk_bf16_f32 v72, v72, v202
	v_cvt_pk_bf16_f32 v74, v203, v74
	s_andn2_b64 vcc, exec, s[12:13]
	s_cbranch_vccnz .La_pv_nowrite
	s_andn2_b32 s14, 1, s9
	s_mul_i32 s14, s14, 0x9000
	v_add_u32_e32 v0, s14, v113
	s_waitcnt vmcnt(3)
	ds_write_b128 v0, v[80:83]
	s_waitcnt vmcnt(1)
	ds_write_b128 v0, v[92:95] offset:9216
	ds_write_b128 v0, v[104:107] offset:18432
	s_waitcnt vmcnt(0)
	ds_write_b128 v0, v[108:111] offset:27648
	s_setprio 1
	s_waitcnt lgkmcnt(10)
	v_mfma_f32_32x32x16_bf16 v[32:47], v[48:51], v[2:5], v[32:47]
	v_mfma_f32_32x32x16_bf16 v[16:31], v[6:9], v[2:5], v[16:31]
	s_waitcnt lgkmcnt(9)
	v_mfma_f32_32x32x16_bf16 v[32:47], v[52:55], v[10:13], v[32:47]
	s_waitcnt lgkmcnt(8)
	v_mfma_f32_32x32x16_bf16 v[16:31], v[56:59], v[10:13], v[16:31]
	s_waitcnt lgkmcnt(7)
	v_mfma_f32_32x32x16_bf16 v[32:47], v[64:67], v[60:63], v[32:47]
	s_waitcnt lgkmcnt(6)
	v_mfma_f32_32x32x16_bf16 v[16:31], v[68:71], v[60:63], v[16:31]
	s_waitcnt lgkmcnt(5)
	v_mfma_f32_32x32x16_bf16 v[32:47], v[76:79], v[72:75], v[32:47]
	s_waitcnt lgkmcnt(4)
	v_mfma_f32_32x32x16_bf16 v[16:31], v[204:207], v[72:75], v[16:31]
	s_setprio 0
	s_branch .LBB0_488
.La_pv_nowrite:
	s_setprio 1
	s_waitcnt lgkmcnt(6)
	v_mfma_f32_32x32x16_bf16 v[32:47], v[48:51], v[2:5], v[32:47]
	v_mfma_f32_32x32x16_bf16 v[16:31], v[6:9], v[2:5], v[16:31]
	s_waitcnt lgkmcnt(5)
	v_mfma_f32_32x32x16_bf16 v[32:47], v[52:55], v[10:13], v[32:47]
	s_waitcnt lgkmcnt(4)
	v_mfma_f32_32x32x16_bf16 v[16:31], v[56:59], v[10:13], v[16:31]
	s_waitcnt lgkmcnt(3)
	v_mfma_f32_32x32x16_bf16 v[32:47], v[64:67], v[60:63], v[32:47]
	s_waitcnt lgkmcnt(2)
	v_mfma_f32_32x32x16_bf16 v[16:31], v[68:71], v[60:63], v[16:31]
	s_waitcnt lgkmcnt(1)
	v_mfma_f32_32x32x16_bf16 v[32:47], v[76:79], v[72:75], v[32:47]
	s_waitcnt lgkmcnt(0)
	v_mfma_f32_32x32x16_bf16 v[16:31], v[204:207], v[72:75], v[16:31]
	s_setprio 0
